# lora epilogue bias loads hoisted; conv input tile loads batched (8 in flight); MLA attention row-max via permlane swaps instead of ds_bpermute
# baseline (speedup 1.0000x reference)
; DEV float sigmoidf_(float v) { return __builtin_amdgcn_rcpf(1.0f + __expf(-v)); }
; DEV void store4(bf16_t* p, f32x4 v) { *(u32x2*)p = (u32x2){pk_bf16(v[0], v[1]), pk_bf16(v[2], v[3])}; }
; template <int MI> DEV void mma_ktile(f32x4 (&acc)[MI][4], const bf16_t* sA, const bf16_t* sB, int wr, int wc, int fr, int fq) {
; #pragma unroll
;     for (int ks = 0; ks < 2; ++ks) {
;         bf16x8 af[MI], bfr[4];
; #pragma unroll
;         for (int mi = 0; mi < MI; ++mi) af[mi] = *(const bf16x8*)(sA + (wr * 16 * MI + mi * 16 + fr) * LDSK + ks * 32 + fq * 8);
; #pragma unroll
;         for (int ni = 0; ni < 4; ++ni) bfr[ni] = *(const bf16x8*)(sB + (wc * 64 + ni * 16 + fr) * LDSK + ks * 32 + fq * 8);
; #pragma unroll
;         for (int mi = 0; mi < MI; ++mi)
; #pragma unroll
;             for (int ni = 0; ni < 4; ++ni) acc[mi][ni] = __builtin_amdgcn_mfma_f32_16x16x32_bf16(bfr[ni], af[mi], acc[mi][ni], 0, 0, 0);
;     }
; }
; DEV void lora_item(const Params& p, int l, int mt, int which, char* smem) {
;     ...
;     for (int nt = 0; nt < 4; ++nt) {
;         f32x4 acc[4][4]; zero_acc<4>(acc);
;         mma_ktile<4>(acc, sA, sB + nt * 128 * LDSK, wr, wc, fr, fq);
; #pragma unroll
;         for (int mi = 0; mi < 4; ++mi) { const size_t row = (size_t)mt * 256 + wr * 64 + mi * 16 + fr;
; #pragma unroll
;             for (int ni = 0; ni < 4; ++ni) { const int col = nt * 128 + wc * 64 + ni * 16 + fq * 4; const f32x4 bz = *(const f32x4*)(bias + col); f32x4 v = acc[mi][ni] + bz;
; #pragma unroll
;                 for (int r = 0; r < 4; ++r) { const float sg = sigmoidf_(v[r]); v[r] = which ? sg : 0.6065306597f * sg; }
;                 store4(ea + row * 1024 + col, v); } }
.LBB0_344:
	global_load_dwordx4 v[188:191], v[100:101], off offset:-128
	global_load_dwordx4 v[192:195], v[100:101], off offset:-64
	global_load_dwordx4 v[196:199], v[100:101], off
	global_load_dwordx4 v[200:203], v[100:101], off offset:64
	ds_read_b128 v[32:35], v104
	ds_read_b128 v[36:39], v104 offset:2560
	ds_read_b128 v[40:43], v104 offset:5120
	ds_read_b128 v[44:47], v104 offset:7680
	s_mov_b32 s0, 0x2e9b0000
	s_waitcnt lgkmcnt(3)
	v_mfma_f32_16x16x32_bf16 v[48:51], v[32:35], v[0:3], 0
	s_waitcnt lgkmcnt(1)
	v_mfma_f32_16x16x32_bf16 v[56:59], v[40:43], v[0:3], 0
	v_mfma_f32_16x16x32_bf16 v[68:71], v[36:39], v[8:11], 0
	v_mfma_f32_16x16x32_bf16 v[106:109], v[40:43], v[8:11], 0
	v_mfma_f32_16x16x32_bf16 v[122:125], v[40:43], v[16:19], 0
	v_mfma_f32_16x16x32_bf16 v[130:133], v[40:43], v[24:27], 0
	ds_read_b128 v[40:43], v104 offset:64
	ds_read_b128 v[138:141], v104 offset:2624
	ds_read_b128 v[142:145], v104 offset:5184
	ds_read_b128 v[146:149], v104 offset:7744
	v_add_u32_e32 v104, 0x5000, v104
	s_waitcnt lgkmcnt(2)
	v_mfma_f32_16x16x32_bf16 v[72:75], v[138:141], v[12:15], v[68:71]
	s_waitcnt lgkmcnt(1)
	v_mfma_f32_16x16x32_bf16 v[68:71], v[142:145], v[12:15], v[106:109]
	s_nop 2
	v_mfma_f32_16x16x32_bf16 v[150:153], v[40:43], v[4:7], v[48:51]
	v_mfma_f32_16x16x32_bf16 v[64:67], v[32:35], v[8:11], 0
	v_mfma_f32_16x16x32_bf16 v[110:113], v[44:47], v[8:11], 0
	s_waitcnt vmcnt(0)
	v_mov_b64_e32 v[106:107], v[188:189]
	v_mov_b64_e32 v[108:109], v[190:191]
	s_nop 4
	v_pk_add_f32 v[106:107], v[150:151], v[106:107]
	s_nop 0
	v_mul_f32_e32 v105, 0xbfb8aa3b, v106
	v_exp_f32_e32 v105, v105
	v_pk_add_f32 v[102:103], v[152:153], v[108:109]
	v_mfma_f32_16x16x32_bf16 v[76:79], v[40:43], v[12:15], v[64:67]
	v_mul_f32_e32 v102, 0xbfb8aa3b, v102
	v_add_f32_e32 v105, 1.0, v105
	v_rcp_f32_e32 v105, v105
	v_exp_f32_e32 v102, v102
	s_waitcnt lgkmcnt(0)
	v_mfma_f32_16x16x32_bf16 v[64:67], v[146:149], v[12:15], v[110:113]
	v_mul_f32_e32 v106, 0x3f1b4598, v105
	v_cndmask_b32_e64 v105, v105, v106, s[38:39]
	v_mul_f32_e32 v106, 0xbfb8aa3b, v107
	v_exp_f32_e32 v106, v106
	v_add_f32_e32 v102, 1.0, v102
	v_rcp_f32_e32 v102, v102
	v_mfma_f32_16x16x32_bf16 v[52:55], v[36:39], v[0:3], 0
	v_add_f32_e32 v106, 1.0, v106
	v_rcp_f32_e32 v106, v106
	v_mfma_f32_16x16x32_bf16 v[88:91], v[138:141], v[4:7], v[52:55]
	v_mul_f32_e32 v107, 0x3f1b4598, v106
	v_cndmask_b32_e64 v106, v106, v107, s[38:39]
	v_mul_f32_e32 v107, 0x3f1b4598, v102
	v_cndmask_b32_e64 v107, v102, v107, s[38:39]
	v_mul_f32_e32 v102, 0xbfb8aa3b, v103
	v_exp_f32_e32 v102, v102
	v_cvt_pk_bf16_f32 v106, v105, v106
	v_mfma_f32_16x16x32_bf16 v[84:87], v[142:145], v[4:7], v[56:59]
	v_add_f32_e32 v102, 1.0, v102
	v_rcp_f32_e32 v102, v102
	v_mfma_f32_16x16x32_bf16 v[60:63], v[44:47], v[0:3], 0
	v_mul_f32_e32 v103, 0x3f1b4598, v102
	v_cndmask_b32_e64 v108, v102, v103, s[38:39]
	v_lshl_add_u64 v[102:103], v[98:99], 0, s[40:41]
	v_add_co_u32_e32 v110, vcc, s0, v102
	v_cvt_pk_bf16_f32 v107, v107, v108
	s_nop 0
	v_addc_co_u32_e32 v111, vcc, 0, v103, vcc
	global_store_dwordx2 v[110:111], v[106:107], off
	v_mfma_f32_16x16x32_bf16 v[80:83], v[146:149], v[4:7], v[60:63]
	v_mov_b64_e32 v[106:107], v[192:193]
	v_mov_b64_e32 v[108:109], v[194:195]
	v_pk_add_f32 v[88:89], v[88:89], v[106:107]
	s_nop 0
	v_mul_f32_e32 v88, 0xbfb8aa3b, v88
	v_pk_add_f32 v[90:91], v[90:91], v[108:109]
	v_exp_f32_e32 v88, v88
	v_mul_f32_e32 v89, 0xbfb8aa3b, v89
	v_exp_f32_e32 v89, v89
	v_mul_f32_e32 v90, 0xbfb8aa3b, v90
	v_exp_f32_e32 v90, v90
	v_mul_f32_e32 v91, 0xbfb8aa3b, v91
	v_exp_f32_e32 v91, v91
	v_add_f32_e32 v88, 1.0, v88
	v_rcp_f32_e32 v88, v88
	v_add_f32_e32 v89, 1.0, v89
	v_rcp_f32_e32 v89, v89
	v_add_f32_e32 v90, 1.0, v90
	v_rcp_f32_e32 v90, v90
	v_add_f32_e32 v91, 1.0, v91
	v_rcp_f32_e32 v91, v91
	v_mul_f32_e32 v105, 0x3f1b4598, v88
	v_cndmask_b32_e64 v88, v88, v105, s[38:39]
	v_mul_f32_e32 v105, 0x3f1b4598, v89
	v_cndmask_b32_e64 v89, v89, v105, s[38:39]
	v_mul_f32_e32 v105, 0x3f1b4598, v90
	v_cndmask_b32_e64 v90, v90, v105, s[38:39]
	v_mul_f32_e32 v105, 0x3f1b4598, v91
	v_cndmask_b32_e64 v91, v91, v105, s[38:39]
	v_cvt_pk_bf16_f32 v88, v88, v89
	v_cvt_pk_bf16_f32 v89, v90, v91
	global_store_dwordx2 v[110:111], v[88:89], off offset:32
	v_mfma_f32_16x16x32_bf16 v[114:117], v[32:35], v[16:19], 0
	v_mov_b64_e32 v[88:89], v[196:197]
	v_mov_b64_e32 v[90:91], v[198:199]
	v_pk_add_f32 v[84:85], v[84:85], v[88:89]
	s_nop 0
	v_mul_f32_e32 v84, 0xbfb8aa3b, v84
	v_pk_add_f32 v[86:87], v[86:87], v[90:91]
	v_exp_f32_e32 v84, v84
	v_mul_f32_e32 v85, 0xbfb8aa3b, v85
	v_exp_f32_e32 v85, v85
	v_mul_f32_e32 v86, 0xbfb8aa3b, v86
	v_exp_f32_e32 v86, v86
	v_mul_f32_e32 v87, 0xbfb8aa3b, v87
	v_exp_f32_e32 v87, v87
	v_add_f32_e32 v84, 1.0, v84
	v_rcp_f32_e32 v84, v84
	v_add_f32_e32 v85, 1.0, v85
	v_rcp_f32_e32 v85, v85
	v_add_f32_e32 v86, 1.0, v86
	v_rcp_f32_e32 v86, v86
	v_add_f32_e32 v87, 1.0, v87
	v_rcp_f32_e32 v87, v87
	v_mul_f32_e32 v88, 0x3f1b4598, v84
	v_cndmask_b32_e64 v84, v84, v88, s[38:39]
	v_mul_f32_e32 v88, 0x3f1b4598, v85
	v_cndmask_b32_e64 v85, v85, v88, s[38:39]
	v_mul_f32_e32 v88, 0x3f1b4598, v86
	v_cndmask_b32_e64 v86, v86, v88, s[38:39]
	v_mul_f32_e32 v88, 0x3f1b4598, v87
	v_cndmask_b32_e64 v87, v87, v88, s[38:39]
	v_cvt_pk_bf16_f32 v84, v84, v85
	v_cvt_pk_bf16_f32 v85, v86, v87
	global_store_dwordx2 v[110:111], v[84:85], off offset:64
	v_mfma_f32_16x16x32_bf16 v[60:63], v[40:43], v[20:23], v[114:117]
	v_mov_b64_e32 v[84:85], v[200:201]
	v_mov_b64_e32 v[86:87], v[202:203]
	v_pk_add_f32 v[80:81], v[80:81], v[84:85]
	s_nop 0
	v_mul_f32_e32 v80, 0xbfb8aa3b, v80
	v_pk_add_f32 v[82:83], v[82:83], v[86:87]
	v_exp_f32_e32 v80, v80
; DEV float sigmoidf_(float v) { return __builtin_amdgcn_rcpf(1.0f + __expf(-v)); }
; DEV void store4(bf16_t* p, f32x4 v) { *(u32x2*)p = (u32x2){pk_bf16(v[0], v[1]), pk_bf16(v[2], v[3])}; }
; DEV void lora_item(const Params& p, int l, int mt, int which, char* smem) {
;     ...
;         for (int mi = 0; mi < 4; ++mi) { const size_t row = (size_t)mt * 256 + wr * 64 + mi * 16 + fr;
; #pragma unroll
;             for (int ni = 0; ni < 4; ++ni) { const int col = nt * 128 + wc * 64 + ni * 16 + fq * 4; const f32x4 bz = *(const f32x4*)(bias + col); f32x4 v = acc[mi][ni] + bz;
; #pragma unroll
;                 for (int r = 0; r < 4; ++r) { const float sg = sigmoidf_(v[r]); v[r] = which ? sg : 0.6065306597f * sg; }
;                 store4(ea + row * 1024 + col, v); } }
	v_mul_f32_e32 v81, 0xbfb8aa3b, v81
	v_exp_f32_e32 v81, v81
	v_mul_f32_e32 v82, 0xbfb8aa3b, v82
	v_exp_f32_e32 v82, v82
	v_mul_f32_e32 v83, 0xbfb8aa3b, v83
	v_exp_f32_e32 v83, v83
	v_add_f32_e32 v80, 1.0, v80
	v_rcp_f32_e32 v80, v80
	v_add_f32_e32 v81, 1.0, v81
	v_rcp_f32_e32 v81, v81
	v_add_f32_e32 v82, 1.0, v82
	v_rcp_f32_e32 v82, v82
	v_add_f32_e32 v83, 1.0, v83
	v_rcp_f32_e32 v83, v83
	v_mul_f32_e32 v84, 0x3f1b4598, v80
	v_cndmask_b32_e64 v80, v80, v84, s[38:39]
	v_mul_f32_e32 v84, 0x3f1b4598, v81
	v_cndmask_b32_e64 v81, v81, v84, s[38:39]
	v_mul_f32_e32 v84, 0x3f1b4598, v82
	v_cndmask_b32_e64 v82, v82, v84, s[38:39]
	v_mul_f32_e32 v84, 0x3f1b4598, v83
	v_cndmask_b32_e64 v83, v83, v84, s[38:39]
	v_cvt_pk_bf16_f32 v80, v80, v81
	v_cvt_pk_bf16_f32 v81, v82, v83
	global_store_dwordx2 v[110:111], v[80:81], off offset:96
	v_mfma_f32_16x16x32_bf16 v[118:121], v[36:39], v[16:19], 0
	v_mov_b64_e32 v[80:81], v[188:189]
	v_mov_b64_e32 v[82:83], v[190:191]
	v_pk_add_f32 v[76:77], v[76:77], v[80:81]
	s_nop 0
	v_mul_f32_e32 v76, 0xbfb8aa3b, v76
	v_pk_add_f32 v[78:79], v[78:79], v[82:83]
	v_exp_f32_e32 v76, v76
	v_mul_f32_e32 v77, 0xbfb8aa3b, v77
	v_exp_f32_e32 v77, v77
	v_mul_f32_e32 v78, 0xbfb8aa3b, v78
	v_exp_f32_e32 v78, v78
	v_mul_f32_e32 v79, 0xbfb8aa3b, v79
	v_exp_f32_e32 v79, v79
	v_add_f32_e32 v76, 1.0, v76
	v_rcp_f32_e32 v76, v76
	v_add_f32_e32 v77, 1.0, v77
	v_rcp_f32_e32 v77, v77
	v_add_f32_e32 v78, 1.0, v78
	v_rcp_f32_e32 v78, v78
	v_add_f32_e32 v79, 1.0, v79
	v_rcp_f32_e32 v79, v79
	v_mul_f32_e32 v80, 0x3f1b4598, v76
	v_cndmask_b32_e64 v76, v76, v80, s[38:39]
	v_mul_f32_e32 v80, 0x3f1b4598, v77
	v_cndmask_b32_e64 v77, v77, v80, s[38:39]
	v_mul_f32_e32 v80, 0x3f1b4598, v78
	v_cndmask_b32_e64 v78, v78, v80, s[38:39]
	v_mul_f32_e32 v80, 0x3f1b4598, v79
	v_cndmask_b32_e64 v79, v79, v80, s[38:39]
	v_cvt_pk_bf16_f32 v76, v76, v77
	v_cvt_pk_bf16_f32 v77, v78, v79
	v_add_co_u32_e32 v78, vcc, s63, v102
	v_mfma_f32_16x16x32_bf16 v[56:59], v[138:141], v[20:23], v[118:121]
	s_nop 0
	v_addc_co_u32_e32 v79, vcc, 0, v103, vcc
	global_store_dwordx2 v[78:79], v[76:77], off
	v_mfma_f32_16x16x32_bf16 v[52:55], v[142:145], v[20:23], v[122:125]
	v_mov_b64_e32 v[76:77], v[192:193]
	v_mov_b64_e32 v[78:79], v[194:195]
	v_pk_add_f32 v[72:73], v[72:73], v[76:77]
	s_nop 0
	v_mul_f32_e32 v72, 0xbfb8aa3b, v72
	v_exp_f32_e32 v72, v72
	v_pk_add_f32 v[78:79], v[74:75], v[78:79]
	v_mfma_f32_16x16x32_bf16 v[126:129], v[44:47], v[16:19], 0
	v_add_f32_e32 v72, 1.0, v72
	v_rcp_f32_e32 v72, v72
	v_mfma_f32_16x16x32_bf16 v[48:51], v[146:149], v[20:23], v[126:129]
	v_mul_f32_e32 v74, 0x3f1b4598, v72
	v_cndmask_b32_e64 v74, v72, v74, s[38:39]
	v_mul_f32_e32 v72, 0xbfb8aa3b, v73
	v_exp_f32_e32 v72, v72
	v_mfma_f32_16x16x32_bf16 v[32:35], v[32:35], v[24:27], 0
	v_add_f32_e32 v72, 1.0, v72
	v_rcp_f32_e32 v72, v72
	v_mfma_f32_16x16x32_bf16 v[134:137], v[44:47], v[24:27], 0
	v_mul_f32_e32 v73, 0x3f1b4598, v72
	v_cndmask_b32_e64 v75, v72, v73, s[38:39]
	v_mul_f32_e32 v72, 0xbfb8aa3b, v78
	v_exp_f32_e32 v72, v72
	v_cvt_pk_bf16_f32 v74, v74, v75
	v_mfma_f32_16x16x32_bf16 v[44:47], v[40:43], v[28:31], v[32:35]
	v_add_f32_e32 v72, 1.0, v72
	v_rcp_f32_e32 v72, v72
	v_mfma_f32_16x16x32_bf16 v[36:39], v[36:39], v[24:27], 0
	v_mul_f32_e32 v73, 0x3f1b4598, v72
	v_cndmask_b32_e64 v76, v72, v73, s[38:39]
	v_mul_f32_e32 v72, 0xbfb8aa3b, v79
	v_exp_f32_e32 v72, v72
	v_mfma_f32_16x16x32_bf16 v[40:43], v[138:141], v[28:31], v[36:39]
	v_add_f32_e32 v72, 1.0, v72
	v_rcp_f32_e32 v72, v72
	v_mfma_f32_16x16x32_bf16 v[36:39], v[142:145], v[28:31], v[130:133]
	v_mul_f32_e32 v73, 0x3f1b4598, v72
	v_cndmask_b32_e64 v77, v72, v73, s[38:39]
	v_lshl_add_u64 v[72:73], v[96:97], 0, s[40:41]
	v_cvt_pk_bf16_f32 v75, v76, v77
	v_add_co_u32_e32 v76, vcc, s63, v72
	v_mfma_f32_16x16x32_bf16 v[32:35], v[146:149], v[28:31], v[134:137]
	s_nop 0
	v_addc_co_u32_e32 v77, vcc, 0, v73, vcc
	global_store_dwordx2 v[76:77], v[74:75], off
	v_mov_b64_e32 v[74:75], v[196:197]
	v_mov_b64_e32 v[76:77], v[198:199]
	v_pk_add_f32 v[68:69], v[68:69], v[74:75]
	s_nop 0
	v_mul_f32_e32 v68, 0xbfb8aa3b, v68
	v_exp_f32_e32 v68, v68
	v_pk_add_f32 v[70:71], v[70:71], v[76:77]
	v_add_f32_e32 v68, 1.0, v68
	v_rcp_f32_e32 v68, v68
	s_nop 0
	v_mul_f32_e32 v74, 0x3f1b4598, v68
	v_cndmask_b32_e64 v74, v68, v74, s[38:39]
	v_mul_f32_e32 v68, 0xbfb8aa3b, v69
	v_exp_f32_e32 v68, v68
	s_nop 0
	v_add_f32_e32 v68, 1.0, v68
	v_rcp_f32_e32 v68, v68
	s_nop 0
	v_mul_f32_e32 v69, 0x3f1b4598, v68
	v_cndmask_b32_e64 v75, v68, v69, s[38:39]
	v_mul_f32_e32 v68, 0xbfb8aa3b, v70
	v_exp_f32_e32 v68, v68
	v_cvt_pk_bf16_f32 v70, v74, v75
	v_add_f32_e32 v68, 1.0, v68
	v_rcp_f32_e32 v68, v68
	s_nop 0
	v_mul_f32_e32 v69, 0x3f1b4598, v68
	v_cndmask_b32_e64 v76, v68, v69, s[38:39]
	v_mul_f32_e32 v68, 0xbfb8aa3b, v71
	v_exp_f32_e32 v68, v68
	s_nop 0
	v_add_f32_e32 v68, 1.0, v68
	v_rcp_f32_e32 v68, v68
	s_nop 0
	v_mul_f32_e32 v69, 0x3f1b4598, v68
	v_cndmask_b32_e64 v71, v68, v69, s[38:39]
	v_lshl_add_u64 v[68:69], v[94:95], 0, s[40:41]
	v_add_co_u32_e32 v74, vcc, s63, v68
	v_cvt_pk_bf16_f32 v71, v76, v71
	s_nop 0
	v_addc_co_u32_e32 v75, vcc, 0, v69, vcc
	global_store_dwordx2 v[74:75], v[70:71], off
	v_mov_b64_e32 v[74:75], v[200:201]
	v_mov_b64_e32 v[76:77], v[202:203]
	v_pk_add_f32 v[64:65], v[64:65], v[74:75]
	s_nop 0
	v_mul_f32_e32 v64, 0xbfb8aa3b, v64
	v_exp_f32_e32 v64, v64
	v_pk_add_f32 v[66:67], v[66:67], v[76:77]
	v_add_f32_e32 v64, 1.0, v64
	v_rcp_f32_e32 v64, v64
	s_nop 0
	v_mul_f32_e32 v70, 0x3f1b4598, v64
	v_cndmask_b32_e64 v70, v64, v70, s[38:39]
	v_mul_f32_e32 v64, 0xbfb8aa3b, v65
	v_exp_f32_e32 v64, v64
	s_nop 0
	v_add_f32_e32 v64, 1.0, v64
	v_rcp_f32_e32 v64, v64
; DEV float sigmoidf_(float v) { return __builtin_amdgcn_rcpf(1.0f + __expf(-v)); }
; DEV void store4(bf16_t* p, f32x4 v) { *(u32x2*)p = (u32x2){pk_bf16(v[0], v[1]), pk_bf16(v[2], v[3])}; }
; DEV void lora_item(const Params& p, int l, int mt, int which, char* smem) {
;     ...
;         for (int mi = 0; mi < 4; ++mi) { const size_t row = (size_t)mt * 256 + wr * 64 + mi * 16 + fr;
; #pragma unroll
;             for (int ni = 0; ni < 4; ++ni) { const int col = nt * 128 + wc * 64 + ni * 16 + fq * 4; const f32x4 bz = *(const f32x4*)(bias + col); f32x4 v = acc[mi][ni] + bz;
; #pragma unroll
;                 for (int r = 0; r < 4; ++r) { const float sg = sigmoidf_(v[r]); v[r] = which ? sg : 0.6065306597f * sg; }
;                 store4(ea + row * 1024 + col, v); } }
	s_nop 0
	v_mul_f32_e32 v65, 0x3f1b4598, v64
	v_cndmask_b32_e64 v71, v64, v65, s[38:39]
	v_mul_f32_e32 v64, 0xbfb8aa3b, v66
	v_exp_f32_e32 v64, v64
	v_cvt_pk_bf16_f32 v66, v70, v71
	v_add_f32_e32 v64, 1.0, v64
	v_rcp_f32_e32 v64, v64
	s_nop 0
	v_mul_f32_e32 v65, 0x3f1b4598, v64
	v_cndmask_b32_e64 v74, v64, v65, s[38:39]
	v_mul_f32_e32 v64, 0xbfb8aa3b, v67
	v_exp_f32_e32 v64, v64
	s_nop 0
	v_add_f32_e32 v64, 1.0, v64
	v_rcp_f32_e32 v64, v64
	s_nop 0
	v_mul_f32_e32 v65, 0x3f1b4598, v64
	v_cndmask_b32_e64 v67, v64, v65, s[38:39]
	v_lshl_add_u64 v[64:65], v[92:93], 0, s[40:41]
	v_add_co_u32_e32 v70, vcc, s63, v64
	v_cvt_pk_bf16_f32 v67, v74, v67
	s_nop 0
	v_addc_co_u32_e32 v71, vcc, 0, v65, vcc
	global_store_dwordx2 v[70:71], v[66:67], off
	s_add_u32 s40, s40, 0x100
	s_addc_u32 s41, s41, 0
	s_cmpk_lg_i32 s40, 0x400
	v_mov_b64_e32 v[74:75], v[188:189]
	v_mov_b64_e32 v[76:77], v[190:191]
	v_pk_add_f32 v[60:61], v[60:61], v[74:75]
	s_nop 0
	v_mul_f32_e32 v60, 0xbfb8aa3b, v60
	v_pk_add_f32 v[62:63], v[62:63], v[76:77]
	v_exp_f32_e32 v60, v60
	v_mul_f32_e32 v61, 0xbfb8aa3b, v61
	v_exp_f32_e32 v61, v61
	v_mul_f32_e32 v62, 0xbfb8aa3b, v62
	v_exp_f32_e32 v62, v62
	v_mul_f32_e32 v63, 0xbfb8aa3b, v63
	v_exp_f32_e32 v63, v63
	v_add_f32_e32 v60, 1.0, v60
	v_rcp_f32_e32 v60, v60
	v_add_f32_e32 v61, 1.0, v61
	v_rcp_f32_e32 v61, v61
	v_add_f32_e32 v62, 1.0, v62
	v_rcp_f32_e32 v62, v62
	v_add_f32_e32 v63, 1.0, v63
	v_rcp_f32_e32 v63, v63
	v_mul_f32_e32 v66, 0x3f1b4598, v60
	v_cndmask_b32_e64 v60, v60, v66, s[38:39]
	v_mul_f32_e32 v66, 0x3f1b4598, v61
	v_cndmask_b32_e64 v61, v61, v66, s[38:39]
	v_mul_f32_e32 v66, 0x3f1b4598, v62
	v_cndmask_b32_e64 v62, v62, v66, s[38:39]
	v_mul_f32_e32 v66, 0x3f1b4598, v63
	v_cndmask_b32_e64 v63, v63, v66, s[38:39]
	v_cvt_pk_bf16_f32 v60, v60, v61
	v_cvt_pk_bf16_f32 v61, v62, v63
	v_add_co_u32_e32 v62, vcc, s51, v102
	s_nop 1
	v_addc_co_u32_e32 v63, vcc, 0, v103, vcc
	global_store_dwordx2 v[62:63], v[60:61], off
	v_mov_b64_e32 v[60:61], v[192:193]
	v_mov_b64_e32 v[62:63], v[194:195]
	v_pk_add_f32 v[56:57], v[56:57], v[60:61]
	s_nop 0
	v_mul_f32_e32 v56, 0xbfb8aa3b, v56
	v_pk_add_f32 v[58:59], v[58:59], v[62:63]
	v_exp_f32_e32 v56, v56
	v_mul_f32_e32 v57, 0xbfb8aa3b, v57
	v_exp_f32_e32 v57, v57
	v_mul_f32_e32 v58, 0xbfb8aa3b, v58
	v_exp_f32_e32 v58, v58
	v_mul_f32_e32 v59, 0xbfb8aa3b, v59
	v_exp_f32_e32 v59, v59
	v_add_f32_e32 v56, 1.0, v56
	v_rcp_f32_e32 v56, v56
	v_add_f32_e32 v57, 1.0, v57
	v_rcp_f32_e32 v57, v57
	v_add_f32_e32 v58, 1.0, v58
	v_rcp_f32_e32 v58, v58
	v_add_f32_e32 v59, 1.0, v59
	v_rcp_f32_e32 v59, v59
	v_mul_f32_e32 v60, 0x3f1b4598, v56
	v_cndmask_b32_e64 v56, v56, v60, s[38:39]
	v_mul_f32_e32 v60, 0x3f1b4598, v57
	v_cndmask_b32_e64 v57, v57, v60, s[38:39]
	v_mul_f32_e32 v60, 0x3f1b4598, v58
	v_cndmask_b32_e64 v58, v58, v60, s[38:39]
	v_mul_f32_e32 v60, 0x3f1b4598, v59
	v_cndmask_b32_e64 v59, v59, v60, s[38:39]
	v_cvt_pk_bf16_f32 v56, v56, v57
	v_cvt_pk_bf16_f32 v57, v58, v59
	v_add_co_u32_e32 v58, vcc, s51, v72
	s_nop 1
	v_addc_co_u32_e32 v59, vcc, 0, v73, vcc
	global_store_dwordx2 v[58:59], v[56:57], off
	v_mov_b64_e32 v[56:57], v[196:197]
	v_mov_b64_e32 v[58:59], v[198:199]
	v_pk_add_f32 v[52:53], v[52:53], v[56:57]
	s_nop 0
	v_mul_f32_e32 v52, 0xbfb8aa3b, v52
	v_pk_add_f32 v[54:55], v[54:55], v[58:59]
	v_exp_f32_e32 v52, v52
	v_mul_f32_e32 v53, 0xbfb8aa3b, v53
	v_exp_f32_e32 v53, v53
	v_mul_f32_e32 v54, 0xbfb8aa3b, v54
	v_exp_f32_e32 v54, v54
	v_mul_f32_e32 v55, 0xbfb8aa3b, v55
	v_exp_f32_e32 v55, v55
	v_add_f32_e32 v52, 1.0, v52
	v_rcp_f32_e32 v52, v52
	v_add_f32_e32 v53, 1.0, v53
	v_rcp_f32_e32 v53, v53
	v_add_f32_e32 v54, 1.0, v54
	v_rcp_f32_e32 v54, v54
	v_add_f32_e32 v55, 1.0, v55
	v_rcp_f32_e32 v55, v55
	v_mul_f32_e32 v56, 0x3f1b4598, v52
	v_cndmask_b32_e64 v52, v52, v56, s[38:39]
	v_mul_f32_e32 v56, 0x3f1b4598, v53
	v_cndmask_b32_e64 v53, v53, v56, s[38:39]
	v_mul_f32_e32 v56, 0x3f1b4598, v54
	v_cndmask_b32_e64 v54, v54, v56, s[38:39]
	v_mul_f32_e32 v56, 0x3f1b4598, v55
	v_cndmask_b32_e64 v55, v55, v56, s[38:39]
	v_cvt_pk_bf16_f32 v52, v52, v53
	v_cvt_pk_bf16_f32 v53, v54, v55
	v_add_co_u32_e32 v54, vcc, s51, v68
	s_nop 1
	v_addc_co_u32_e32 v55, vcc, 0, v69, vcc
	global_store_dwordx2 v[54:55], v[52:53], off
	v_mov_b64_e32 v[52:53], v[200:201]
	v_mov_b64_e32 v[54:55], v[202:203]
	v_pk_add_f32 v[48:49], v[48:49], v[52:53]
	s_nop 0
	v_mul_f32_e32 v48, 0xbfb8aa3b, v48
	v_pk_add_f32 v[50:51], v[50:51], v[54:55]
	v_exp_f32_e32 v48, v48
	v_mul_f32_e32 v49, 0xbfb8aa3b, v49
	v_exp_f32_e32 v49, v49
	v_mul_f32_e32 v50, 0xbfb8aa3b, v50
	v_exp_f32_e32 v50, v50
	v_mul_f32_e32 v51, 0xbfb8aa3b, v51
	v_exp_f32_e32 v51, v51
	v_add_f32_e32 v48, 1.0, v48
	v_rcp_f32_e32 v48, v48
	v_add_f32_e32 v49, 1.0, v49
	v_rcp_f32_e32 v49, v49
	v_add_f32_e32 v50, 1.0, v50
	v_rcp_f32_e32 v50, v50
	v_add_f32_e32 v51, 1.0, v51
	v_rcp_f32_e32 v51, v51
	v_mul_f32_e32 v52, 0x3f1b4598, v48
	v_cndmask_b32_e64 v48, v48, v52, s[38:39]
	v_mul_f32_e32 v52, 0x3f1b4598, v49
	v_cndmask_b32_e64 v49, v49, v52, s[38:39]
	v_mul_f32_e32 v52, 0x3f1b4598, v50
; DEV float sigmoidf_(float v) { return __builtin_amdgcn_rcpf(1.0f + __expf(-v)); }
; DEV void store4(bf16_t* p, f32x4 v) { *(u32x2*)p = (u32x2){pk_bf16(v[0], v[1]), pk_bf16(v[2], v[3])}; }
; DEV void lora_item(const Params& p, int l, int mt, int which, char* smem) {
;     ...
;         for (int mi = 0; mi < 4; ++mi) { const size_t row = (size_t)mt * 256 + wr * 64 + mi * 16 + fr;
; #pragma unroll
;             for (int ni = 0; ni < 4; ++ni) { const int col = nt * 128 + wc * 64 + ni * 16 + fq * 4; const f32x4 bz = *(const f32x4*)(bias + col); f32x4 v = acc[mi][ni] + bz;
; #pragma unroll
;                 for (int r = 0; r < 4; ++r) { const float sg = sigmoidf_(v[r]); v[r] = which ? sg : 0.6065306597f * sg; }
;                 store4(ea + row * 1024 + col, v); } }
;     }
	v_cndmask_b32_e64 v50, v50, v52, s[38:39]
	v_mul_f32_e32 v52, 0x3f1b4598, v51
	v_cndmask_b32_e64 v51, v51, v52, s[38:39]
	v_cvt_pk_bf16_f32 v48, v48, v49
	v_cvt_pk_bf16_f32 v49, v50, v51
	v_add_co_u32_e32 v50, vcc, s51, v64
	s_nop 1
	v_addc_co_u32_e32 v51, vcc, 0, v65, vcc
	global_store_dwordx2 v[50:51], v[48:49], off
	v_mov_b64_e32 v[48:49], v[188:189]
	v_mov_b64_e32 v[50:51], v[190:191]
	v_pk_add_f32 v[44:45], v[44:45], v[48:49]
	s_nop 0
	v_mul_f32_e32 v44, 0xbfb8aa3b, v44
	v_pk_add_f32 v[46:47], v[46:47], v[50:51]
	v_exp_f32_e32 v44, v44
	v_mul_f32_e32 v45, 0xbfb8aa3b, v45
	v_exp_f32_e32 v45, v45
	v_mul_f32_e32 v46, 0xbfb8aa3b, v46
	v_exp_f32_e32 v46, v46
	v_mul_f32_e32 v47, 0xbfb8aa3b, v47
	v_exp_f32_e32 v47, v47
	v_add_f32_e32 v44, 1.0, v44
	v_rcp_f32_e32 v44, v44
	v_add_f32_e32 v45, 1.0, v45
	v_rcp_f32_e32 v45, v45
	v_add_f32_e32 v46, 1.0, v46
	v_rcp_f32_e32 v46, v46
	v_add_f32_e32 v47, 1.0, v47
	v_rcp_f32_e32 v47, v47
	v_mul_f32_e32 v48, 0x3f1b4598, v44
	v_cndmask_b32_e64 v44, v44, v48, s[38:39]
	v_mul_f32_e32 v48, 0x3f1b4598, v45
	v_cndmask_b32_e64 v45, v45, v48, s[38:39]
	v_mul_f32_e32 v48, 0x3f1b4598, v46
	v_cndmask_b32_e64 v46, v46, v48, s[38:39]
	v_mul_f32_e32 v48, 0x3f1b4598, v47
	v_cndmask_b32_e64 v47, v47, v48, s[38:39]
	v_cvt_pk_bf16_f32 v44, v44, v45
	v_cvt_pk_bf16_f32 v45, v46, v47
	v_add_co_u32_e32 v46, vcc, s16, v102
	s_nop 1
	v_addc_co_u32_e32 v47, vcc, 0, v103, vcc
	global_store_dwordx2 v[46:47], v[44:45], off
	v_mov_b64_e32 v[44:45], v[192:193]
	v_mov_b64_e32 v[46:47], v[194:195]
	v_pk_add_f32 v[40:41], v[40:41], v[44:45]
	s_nop 0
	v_mul_f32_e32 v40, 0xbfb8aa3b, v40
	v_pk_add_f32 v[42:43], v[42:43], v[46:47]
	v_exp_f32_e32 v40, v40
	v_mul_f32_e32 v41, 0xbfb8aa3b, v41
	v_exp_f32_e32 v41, v41
	v_mul_f32_e32 v42, 0xbfb8aa3b, v42
	v_exp_f32_e32 v42, v42
	v_mul_f32_e32 v43, 0xbfb8aa3b, v43
	v_exp_f32_e32 v43, v43
	v_add_f32_e32 v40, 1.0, v40
	v_rcp_f32_e32 v40, v40
	v_add_f32_e32 v41, 1.0, v41
	v_rcp_f32_e32 v41, v41
	v_add_f32_e32 v42, 1.0, v42
	v_rcp_f32_e32 v42, v42
	v_add_f32_e32 v43, 1.0, v43
	v_rcp_f32_e32 v43, v43
	v_mul_f32_e32 v44, 0x3f1b4598, v40
	v_cndmask_b32_e64 v40, v40, v44, s[38:39]
	v_mul_f32_e32 v44, 0x3f1b4598, v41
	v_cndmask_b32_e64 v41, v41, v44, s[38:39]
	v_mul_f32_e32 v44, 0x3f1b4598, v42
	v_cndmask_b32_e64 v42, v42, v44, s[38:39]
	v_mul_f32_e32 v44, 0x3f1b4598, v43
	v_cndmask_b32_e64 v43, v43, v44, s[38:39]
	v_cvt_pk_bf16_f32 v40, v40, v41
	v_cvt_pk_bf16_f32 v41, v42, v43
	v_add_co_u32_e32 v42, vcc, s16, v72
	s_nop 1
	v_addc_co_u32_e32 v43, vcc, 0, v73, vcc
	global_store_dwordx2 v[42:43], v[40:41], off
	v_mov_b64_e32 v[40:41], v[196:197]
	v_mov_b64_e32 v[42:43], v[198:199]
	v_pk_add_f32 v[36:37], v[36:37], v[40:41]
	s_nop 0
	v_mul_f32_e32 v36, 0xbfb8aa3b, v36
	v_pk_add_f32 v[38:39], v[38:39], v[42:43]
	v_exp_f32_e32 v36, v36
	v_mul_f32_e32 v37, 0xbfb8aa3b, v37
	v_exp_f32_e32 v37, v37
	v_mul_f32_e32 v38, 0xbfb8aa3b, v38
	v_exp_f32_e32 v38, v38
	v_mul_f32_e32 v39, 0xbfb8aa3b, v39
	v_exp_f32_e32 v39, v39
	v_add_f32_e32 v36, 1.0, v36
	v_rcp_f32_e32 v36, v36
	v_add_f32_e32 v37, 1.0, v37
	v_rcp_f32_e32 v37, v37
	v_add_f32_e32 v38, 1.0, v38
	v_rcp_f32_e32 v38, v38
	v_add_f32_e32 v39, 1.0, v39
	v_rcp_f32_e32 v39, v39
	v_mul_f32_e32 v40, 0x3f1b4598, v36
	v_cndmask_b32_e64 v36, v36, v40, s[38:39]
	v_mul_f32_e32 v40, 0x3f1b4598, v37
	v_cndmask_b32_e64 v37, v37, v40, s[38:39]
	v_mul_f32_e32 v40, 0x3f1b4598, v38
	v_cndmask_b32_e64 v38, v38, v40, s[38:39]
	v_mul_f32_e32 v40, 0x3f1b4598, v39
	v_cndmask_b32_e64 v39, v39, v40, s[38:39]
	v_cvt_pk_bf16_f32 v36, v36, v37
	v_cvt_pk_bf16_f32 v37, v38, v39
	v_add_co_u32_e32 v38, vcc, s16, v68
	s_nop 1
	v_addc_co_u32_e32 v39, vcc, 0, v69, vcc
	global_store_dwordx2 v[38:39], v[36:37], off
	v_lshl_add_u64 v[100:101], v[100:101], 0, s[30:31]
	v_mov_b64_e32 v[36:37], v[200:201]
	v_mov_b64_e32 v[38:39], v[202:203]
	v_pk_add_f32 v[32:33], v[32:33], v[36:37]
	s_nop 0
	v_mul_f32_e32 v32, 0xbfb8aa3b, v32
	v_pk_add_f32 v[34:35], v[34:35], v[38:39]
	v_exp_f32_e32 v32, v32
	v_mul_f32_e32 v33, 0xbfb8aa3b, v33
	v_exp_f32_e32 v33, v33
	v_mul_f32_e32 v34, 0xbfb8aa3b, v34
	v_exp_f32_e32 v34, v34
	v_mul_f32_e32 v35, 0xbfb8aa3b, v35
	v_exp_f32_e32 v35, v35
	v_add_f32_e32 v32, 1.0, v32
	v_rcp_f32_e32 v32, v32
	v_add_f32_e32 v33, 1.0, v33
	v_rcp_f32_e32 v33, v33
	v_add_f32_e32 v34, 1.0, v34
	v_rcp_f32_e32 v34, v34
	v_add_f32_e32 v35, 1.0, v35
	v_rcp_f32_e32 v35, v35
	v_mul_f32_e32 v36, 0x3f1b4598, v32
	v_cndmask_b32_e64 v32, v32, v36, s[38:39]
	v_mul_f32_e32 v36, 0x3f1b4598, v33
	v_cndmask_b32_e64 v33, v33, v36, s[38:39]
	v_mul_f32_e32 v36, 0x3f1b4598, v34
	v_cndmask_b32_e64 v34, v34, v36, s[38:39]
	v_mul_f32_e32 v36, 0x3f1b4598, v35
	v_cndmask_b32_e64 v35, v35, v36, s[38:39]
	v_cvt_pk_bf16_f32 v32, v32, v33
	v_cvt_pk_bf16_f32 v33, v34, v35
	v_add_co_u32_e32 v34, vcc, s16, v64
	s_nop 1
	v_addc_co_u32_e32 v35, vcc, 0, v65, vcc
	global_store_dwordx2 v[34:35], v[32:33], off
	s_cbranch_scc1 .LBB0_344
	s_add_i32 s19, s19, s18
	s_xor_b64 s[96:97], s[96:97], s[6:7]
	s_cmpk_gt_i32 s19, 0x1ff
	s_cbranch_scc0 .LBB0_327

; DEV void conv_item(const Params& p, int l, int tile, char* smem, int dry) {
;     ...
;     __syncthreads();
;     for (int c = tid; c < 62 * 64; c += NTHR) { const int row = c >> 6, ch = c & 63; const int srel = s0 - 30 + row;
;         u32x4 v = (u32x4){0u, 0u, 0u, 0u};
;         if (srel >= 0) v = *(const u32x4*)(cu + (size_t)(t0 - 30 + row) * 512 + ch * 8);
;         *(u32x4*)(sin_ + row * 512 + ch * 8) = v; }
.LBB0_393:
	v_mov_b32_e32 v16, v163
	s_movk_i32 s0, 0xf80
	s_nop 0
	v_cmp_gt_i32_e32 vcc, s0, v16
	s_barrier
	s_and_saveexec_b64 s[0:1], vcc
	s_cbranch_execz .LBB0_398
	s_lshl_b32 s4, s44, 5
	v_lshlrev_b32_e32 v0, 4, v16
	s_and_b32 s5, s4, 0x7e0
	v_and_b32_e32 v160, 0x3f0, v0
	s_sub_i32 s8, 29, s5
	s_sub_i32 s9, s4, 30
	v_lshl_add_u64 v[4:5], s[40:41], 0, v[160:161]
	v_add_u32_e32 v6, 0, v160
	v_ashrrev_i32_e32 v8, 6, v16
	v_mov_b64_e32 v[104:105], 0
	v_mov_b64_e32 v[106:107], 0
	v_mov_b64_e32 v[108:109], 0
	v_mov_b64_e32 v[110:111], 0
	v_mov_b64_e32 v[112:113], 0
	v_mov_b64_e32 v[114:115], 0
	v_mov_b64_e32 v[116:117], 0
	v_mov_b64_e32 v[118:119], 0
	v_mov_b64_e32 v[120:121], 0
	v_mov_b64_e32 v[122:123], 0
	v_mov_b64_e32 v[124:125], 0
	v_mov_b64_e32 v[126:127], 0
	v_mov_b64_e32 v[128:129], 0
	v_mov_b64_e32 v[130:131], 0
	v_mov_b64_e32 v[132:133], 0
	v_mov_b64_e32 v[134:135], 0
	v_mov_b32_e32 v9, v8
	v_cmp_lt_i32_e32 vcc, s8, v9
	s_and_saveexec_b64 s[6:7], vcc
	v_add_u32_e32 v10, s9, v9
	v_ashrrev_i32_e32 v11, 31, v10
	v_lshlrev_b64 v[10:11], 10, v[10:11]
	v_lshl_add_u64 v[10:11], v[4:5], 0, v[10:11]
	global_load_dwordx4 v[104:107], v[10:11], off
	s_or_b64 exec, exec, s[6:7]
	v_add_u32_e32 v9, 8, v8
	v_cmp_lt_i32_e32 vcc, s8, v9
	s_and_saveexec_b64 s[6:7], vcc
	v_add_u32_e32 v10, s9, v9
	v_ashrrev_i32_e32 v11, 31, v10
	v_lshlrev_b64 v[10:11], 10, v[10:11]
	v_lshl_add_u64 v[10:11], v[4:5], 0, v[10:11]
	global_load_dwordx4 v[108:111], v[10:11], off
	s_or_b64 exec, exec, s[6:7]
	v_add_u32_e32 v9, 16, v8
	v_cmp_lt_i32_e32 vcc, s8, v9
	s_and_saveexec_b64 s[6:7], vcc
	v_add_u32_e32 v10, s9, v9
	v_ashrrev_i32_e32 v11, 31, v10
	v_lshlrev_b64 v[10:11], 10, v[10:11]
	v_lshl_add_u64 v[10:11], v[4:5], 0, v[10:11]
	global_load_dwordx4 v[112:115], v[10:11], off
	s_or_b64 exec, exec, s[6:7]
	v_add_u32_e32 v9, 24, v8
	v_cmp_lt_i32_e32 vcc, s8, v9
	s_and_saveexec_b64 s[6:7], vcc
	v_add_u32_e32 v10, s9, v9
	v_ashrrev_i32_e32 v11, 31, v10
	v_lshlrev_b64 v[10:11], 10, v[10:11]
	v_lshl_add_u64 v[10:11], v[4:5], 0, v[10:11]
	global_load_dwordx4 v[116:119], v[10:11], off
	s_or_b64 exec, exec, s[6:7]
	v_add_u32_e32 v9, 32, v8
	v_cmp_lt_i32_e32 vcc, s8, v9
	s_and_saveexec_b64 s[6:7], vcc
	v_add_u32_e32 v10, s9, v9
	v_ashrrev_i32_e32 v11, 31, v10
	v_lshlrev_b64 v[10:11], 10, v[10:11]
	v_lshl_add_u64 v[10:11], v[4:5], 0, v[10:11]
	global_load_dwordx4 v[120:123], v[10:11], off
	s_or_b64 exec, exec, s[6:7]
	v_add_u32_e32 v9, 40, v8
	v_cmp_lt_i32_e32 vcc, s8, v9
	s_and_saveexec_b64 s[6:7], vcc
	v_add_u32_e32 v10, s9, v9
	v_ashrrev_i32_e32 v11, 31, v10
	v_lshlrev_b64 v[10:11], 10, v[10:11]
	v_lshl_add_u64 v[10:11], v[4:5], 0, v[10:11]
	global_load_dwordx4 v[124:127], v[10:11], off
	s_or_b64 exec, exec, s[6:7]
	v_add_u32_e32 v9, 48, v8
	v_cmp_lt_i32_e32 vcc, s8, v9
	s_and_saveexec_b64 s[6:7], vcc
	v_add_u32_e32 v10, s9, v9
	v_ashrrev_i32_e32 v11, 31, v10
	v_lshlrev_b64 v[10:11], 10, v[10:11]
	v_lshl_add_u64 v[10:11], v[4:5], 0, v[10:11]
	global_load_dwordx4 v[128:131], v[10:11], off
	s_or_b64 exec, exec, s[6:7]
	v_add_u32_e32 v9, 56, v8
	v_cmp_gt_i32_e32 vcc, 0x180, v16
	s_mov_b64 s[6:7], vcc
	v_cmp_lt_i32_e32 vcc, s8, v9
	s_and_b64 vcc, vcc, s[6:7]
	s_and_saveexec_b64 s[6:7], vcc
	v_add_u32_e32 v10, s9, v9
	v_ashrrev_i32_e32 v11, 31, v10
	v_lshlrev_b64 v[10:11], 10, v[10:11]
	v_lshl_add_u64 v[10:11], v[4:5], 0, v[10:11]
	global_load_dwordx4 v[132:135], v[10:11], off
	s_or_b64 exec, exec, s[6:7]
	v_lshl_add_u32 v9, v8, 10, v6
	s_waitcnt vmcnt(0)
	ds_write_b128 v9, v[104:107]
	ds_write_b128 v9, v[108:111] offset:8192
	ds_write_b128 v9, v[112:115] offset:16384
	ds_write_b128 v9, v[116:119] offset:24576
	ds_write_b128 v9, v[120:123] offset:32768
	ds_write_b128 v9, v[124:127] offset:40960
	ds_write_b128 v9, v[128:131] offset:49152
	v_cmp_gt_i32_e32 vcc, 0x180, v16
	s_and_saveexec_b64 s[6:7], vcc
	ds_write_b128 v9, v[132:135] offset:57344
	s_or_b64 exec, exec, s[6:7]

;     ...
; #pragma unroll
;             for (int ni = 0; ni < 4; ++ni) mx = fmaxf(mx, fmaxf(fmaxf(s[mi][ni][0], s[mi][ni][1]), fmaxf(s[mi][ni][2], s[mi][ni][3])));
;             mx = fmaxf(mx, __shfl_xor(mx, 16)); mx = fmaxf(mx, __shfl_xor(mx, 32));
;             const float mnew = fmaxf(mrun[mi], mx);
;             const float mc = mnew * scale_log2;
;             float ps = 0.f;
; #pragma unroll
;             for (int ni = 0; ni < 4; ++ni)
; #pragma unroll
;                 for (int r = 0; r < 4; ++r) { const float pv = __builtin_amdgcn_exp2f(__builtin_fmaf(s[mi][ni][r], scale_log2, -mc)); s[mi][ni][r] = pv; ps += pv; }
;             if (__builtin_amdgcn_ballot_w64(mnew > mrun[mi]) != 0ull) {
;                 const float alpha = __builtin_amdgcn_exp2f((mrun[mi] - mnew) * scale_log2);
;                 lrun[mi] *= alpha;
; #pragma unroll
;                 for (int di = 0; di < DV / 16; ++di) o[mi][di] *= alpha;
.LBB0_711:
	s_or_b64 exec, exec, s[0:1]
	v_mbcnt_hi_u32_b32 v102, -1, v182
	v_and_b32_e32 v115, 64, v102
	v_xor_b32_e32 v103, 16, v102
	v_add_u32_e32 v115, 64, v115
	v_cmp_lt_i32_e32 vcc, v103, v115
	v_xor_b32_e32 v132, 32, v102
	v_max_f32_e32 v133, v74, v74
	v_cndmask_b32_e32 v103, v102, v103, vcc
	v_cmp_lt_i32_e32 vcc, v132, v115
	v_max_f32_e32 v115, v79, v79
	v_max_f32_e32 v151, v94, v94
	v_cndmask_b32_e32 v102, v102, v132, vcc
	v_max_f32_e32 v132, v78, v78
	v_max_f32_e32 v115, v132, v115
	v_max_f32_e32 v132, v75, v75
	v_max_f32_e32 v132, v133, v132
	v_max3_f32 v115, v76, v77, v115
	v_max3_f32 v132, v72, v73, v132
	v_max3_f32 v115, v115, s17, v132
	v_max_f32_e32 v132, v87, v87
	v_max_f32_e32 v133, v86, v86
	v_max_f32_e32 v132, v133, v132
	v_max_f32_e32 v133, v95, v95
	v_max_f32_e32 v133, v151, v133
	v_max3_f32 v132, v84, v85, v132
	v_max3_f32 v133, v92, v93, v133
	v_lshlrev_b32_e32 v103, 2, v103
	v_max3_f32 v115, v115, v132, v133
	v_mov_b32_e32 v132, v115
	v_lshlrev_b32_e32 v102, 2, v102
	s_nop 1
	v_permlane16_swap_b32_e32 v132, v115
	s_nop 0
	v_max_f32_e32 v115, v115, v132
	v_mov_b32_e32 v132, v115
	s_nop 1
	v_permlane32_swap_b32_e32 v132, v115
	s_nop 0
	v_max3_f32 v132, v100, v115, v132
	v_cmp_gt_f32_e32 vcc, v132, v100
	s_cbranch_vccz .LBB0_713
	v_sub_f32_e32 v100, v100, v132
	v_mul_f32_e32 v100, 0x3e16c740, v100
	v_exp_f32_e32 v100, v100
	s_nop 0
	v_mul_f32_e32 v120, v120, v100
	v_pk_mul_f32 v[22:23], v[22:23], v[100:101] op_sel_hi:[1,0]
	v_pk_mul_f32 v[20:21], v[20:21], v[100:101] op_sel_hi:[1,0]
	v_pk_mul_f32 v[14:15], v[14:15], v[100:101] op_sel_hi:[1,0]
	v_pk_mul_f32 v[12:13], v[12:13], v[100:101] op_sel_hi:[1,0]
	v_pk_mul_f32 v[6:7], v[6:7], v[100:101] op_sel_hi:[1,0]
	v_pk_mul_f32 v[4:5], v[4:5], v[100:101] op_sel_hi:[1,0]
	v_pk_mul_f32 v[18:19], v[18:19], v[100:101] op_sel_hi:[1,0]
	v_pk_mul_f32 v[16:17], v[16:17], v[100:101] op_sel_hi:[1,0]

;     ...
; #pragma unroll
;             for (int ni = 0; ni < 4; ++ni) mx = fmaxf(mx, fmaxf(fmaxf(s[mi][ni][0], s[mi][ni][1]), fmaxf(s[mi][ni][2], s[mi][ni][3])));
;             mx = fmaxf(mx, __shfl_xor(mx, 16)); mx = fmaxf(mx, __shfl_xor(mx, 32));
;             const float mnew = fmaxf(mrun[mi], mx);
;             const float mc = mnew * scale_log2;
;             float ps = 0.f;
; #pragma unroll
;             for (int ni = 0; ni < 4; ++ni)
; #pragma unroll
;                 for (int r = 0; r < 4; ++r) { const float pv = __builtin_amdgcn_exp2f(__builtin_fmaf(s[mi][ni][r], scale_log2, -mc)); s[mi][ni][r] = pv; ps += pv; }
;             if (__builtin_amdgcn_ballot_w64(mnew > mrun[mi]) != 0ull) {
;                 const float alpha = __builtin_amdgcn_exp2f((mrun[mi] - mnew) * scale_log2);
;                 lrun[mi] *= alpha;
; #pragma unroll
;                 for (int di = 0; di < DV / 16; ++di) o[mi][di] *= alpha;
;             }
.LBB0_715:
	s_or_b64 exec, exec, s[0:1]
	v_mul_f32_e32 v100, 0xbe16c740, v132
	v_fmamk_f32 v76, v76, 0x3e16c740, v100
	v_exp_f32_e32 v76, v76
	v_fmamk_f32 v77, v77, 0x3e16c740, v100
	v_exp_f32_e32 v77, v77
	v_fmamk_f32 v78, v78, 0x3e16c740, v100
	v_exp_f32_e32 v78, v78
	v_fmamk_f32 v79, v79, 0x3e16c740, v100
	v_exp_f32_e32 v79, v79
	v_fmamk_f32 v72, v72, 0x3e16c740, v100
	v_add_f32_e32 v104, 0, v76
	v_exp_f32_e32 v72, v72
	v_fmamk_f32 v73, v73, 0x3e16c740, v100
	v_add_f32_e32 v104, v77, v104
	v_exp_f32_e32 v73, v73
	v_fmamk_f32 v74, v74, 0x3e16c740, v100
	v_add_f32_e32 v104, v78, v104
	v_exp_f32_e32 v74, v74
	v_fmamk_f32 v75, v75, 0x3e16c740, v100
	v_add_f32_e32 v104, v79, v104
	v_exp_f32_e32 v75, v75
	v_fmamk_f32 v84, v84, 0x3e16c740, v100
	v_add_f32_e32 v104, v72, v104
	v_exp_f32_e32 v84, v84
	v_fmamk_f32 v85, v85, 0x3e16c740, v100
	v_add_f32_e32 v104, v73, v104
	v_exp_f32_e32 v85, v85
	v_fmamk_f32 v86, v86, 0x3e16c740, v100
	v_add_f32_e32 v104, v74, v104
	v_exp_f32_e32 v86, v86
	v_fmamk_f32 v87, v87, 0x3e16c740, v100
	v_add_f32_e32 v104, v75, v104
	v_exp_f32_e32 v87, v87
	v_fmamk_f32 v92, v92, 0x3e16c740, v100
	v_add_f32_e32 v104, v84, v104
	v_exp_f32_e32 v92, v92
	v_fmamk_f32 v93, v93, 0x3e16c740, v100
	v_add_f32_e32 v104, v85, v104
	v_exp_f32_e32 v93, v93
	v_fmamk_f32 v94, v94, 0x3e16c740, v100
	v_add_f32_e32 v104, v86, v104
	v_exp_f32_e32 v94, v94
	v_fmac_f32_e32 v100, 0x3e16c740, v95
	v_add_f32_e32 v104, v87, v104
	v_exp_f32_e32 v95, v100
	v_add_f32_e32 v104, v92, v104
	v_add_f32_e32 v104, v93, v104
	v_add_f32_e32 v104, v94, v104
	v_add_f32_e32 v100, v95, v104
	v_add_f32_e32 v120, v100, v120
	v_max_f32_e32 v100, v55, v55
	v_max_f32_e32 v104, v54, v54
	v_max_f32_e32 v100, v104, v100
	v_max_f32_e32 v104, v43, v43
	v_max_f32_e32 v105, v42, v42
	v_max_f32_e32 v104, v105, v104
	v_max3_f32 v100, v52, v53, v100
	v_max3_f32 v104, v40, v41, v104
	v_max3_f32 v100, v100, s17, v104
	v_max_f32_e32 v104, v59, v59
	v_max_f32_e32 v105, v58, v58
	v_max_f32_e32 v104, v105, v104
	v_max_f32_e32 v105, v71, v71
	v_max_f32_e32 v106, v70, v70
	v_max_f32_e32 v105, v106, v105
	v_max3_f32 v104, v56, v57, v104
	v_max3_f32 v105, v68, v69, v105
	v_max3_f32 v100, v100, v104, v105
	v_mov_b32_e32 v103, v100
	s_nop 1
	v_permlane16_swap_b32_e32 v103, v100
	s_nop 0
	v_max_f32_e32 v100, v100, v103
	v_mov_b32_e32 v102, v100
	s_nop 1
	v_permlane32_swap_b32_e32 v102, v100
	s_nop 0
	v_max3_f32 v133, v101, v100, v102
	v_cmp_gt_f32_e32 vcc, v133, v101
	s_cbranch_vccz .LBB0_717
	v_sub_f32_e32 v100, v101, v133
	v_mul_f32_e32 v100, 0x3e16c740, v100
	v_exp_f32_e32 v100, v100
	s_nop 0
	v_mul_f32_e32 v121, v121, v100
	v_pk_mul_f32 v[30:31], v[30:31], v[100:101] op_sel_hi:[1,0]
	v_pk_mul_f32 v[28:29], v[28:29], v[100:101] op_sel_hi:[1,0]
	v_pk_mul_f32 v[10:11], v[10:11], v[100:101] op_sel_hi:[1,0]
	v_pk_mul_f32 v[8:9], v[8:9], v[100:101] op_sel_hi:[1,0]
	v_pk_mul_f32 v[2:3], v[2:3], v[100:101] op_sel_hi:[1,0]
	v_pk_mul_f32 v[0:1], v[0:1], v[100:101] op_sel_hi:[1,0]
	v_pk_mul_f32 v[26:27], v[26:27], v[100:101] op_sel_hi:[1,0]
	v_pk_mul_f32 v[24:25], v[24:25], v[100:101] op_sel_hi:[1,0]
